# v49 = v43 + weight-conversion tiles (phase 0 and layer-1 copy): the four masked f32 tile loads issued together instead of four dependent load/wait/LDS-write blocks
# speedup vs baseline: 1.0127x; 1.0127x over previous
.LBB0_119:
	s_lshr_b32 s4, s79, 6
	s_mul_i32 s4, s6, s4
	s_add_i32 s7, s4, s78
	s_cmp_lt_i32 s80, s7
	s_cselect_b64 s[4:5], -1, 0
	s_cmp_ge_i32 s80, s7
	s_cbranch_scc1 .LBB0_88
	v_cvt_f32_u32_e32 v0, s6
	s_sub_i32 s24, 0, s6
	s_sub_i32 s7, s80, s78
	s_abs_i32 s72, s7
	v_rcp_iflag_f32_e32 v0, v0
	s_ashr_i32 s25, s7, 31
	v_mov_b32_e32 v1, v73
	v_mul_f32_e32 v0, 0x4f7ffffe, v0
	v_cvt_u32_f32_e32 v0, v0
	v_mov_b32_e32 v2, 0
	v_mov_b32_e32 v3, 0
	v_mov_b32_e32 v4, 0
	v_readfirstlane_b32 vcc_lo, v0
	s_mul_i32 s24, s24, vcc_lo
	s_mul_hi_u32 s24, vcc_lo, s24
	s_add_i32 vcc_lo, vcc_lo, s24
	s_mul_hi_u32 s24, s72, vcc_lo
	s_mul_i32 vcc_lo, s24, s6
	s_sub_i32 s72, s72, vcc_lo
	s_add_i32 vcc_hi, s24, 1
	s_sub_i32 vcc_lo, s72, s6
	s_cmp_ge_u32 s72, s6
	s_cselect_b32 s24, vcc_hi, s24
	s_cselect_b32 s72, vcc_lo, s72
	s_add_i32 vcc_lo, s24, 1
	s_cmp_ge_u32 s72, s6
	s_cselect_b32 s24, vcc_lo, s24
	s_xor_b32 s24, s24, s25
	s_sub_i32 s24, s24, s25
	s_lshl_b32 s72, s24, 6
	s_mul_i32 s24, s24, s6
	s_sub_i32 s6, s7, s24
	v_mbcnt_lo_u32_b32 v0, -1, v1
	s_lshl_b32 s6, s6, 6
	v_mbcnt_hi_u32_b32 v0, -1, v0
	v_add_u32_e32 v8, s33, v0
	s_ashr_i32 s7, s6, 31
	s_lshl_b64 s[24:25], s[6:7], 2
	v_lshlrev_b32_e32 v0, 2, v8
	v_and_b32_e32 v0, 60, v0
	s_add_u32 s24, s70, s24
	v_or_b32_e32 v1, s6, v0
	s_addc_u32 s25, s71, s25
	v_lshlrev_b32_e32 v72, 2, v0
	v_cmp_gt_i32_e32 vcc, s73, v1
	v_lshl_add_u64 v[6:7], s[24:25], 0, v[72:73]
	v_ashrrev_i32_e32 v1, 4, v8
	v_mov_b32_e32 v0, 0
	v_mov_b32_e32 v5, 0
	s_barrier
	v_mov_b32_e32 v230, 0
	v_mov_b32_e32 v231, 0
	v_mov_b32_e32 v232, 0
	v_mov_b32_e32 v233, 0
	v_mov_b32_e32 v234, 0
	v_mov_b32_e32 v235, 0
	v_mov_b32_e32 v236, 0
	v_mov_b32_e32 v237, 0
	v_mov_b32_e32 v238, 0
	v_mov_b32_e32 v239, 0
	v_mov_b32_e32 v240, 0
	v_mov_b32_e32 v241, 0
	s_and_saveexec_b64 s[70:71], vcc
	s_cbranch_execz .LBB0_122
	v_add_u32_e32 v2, s72, v1
	v_ashrrev_i32_e32 v5, 31, v2
	v_mad_u64_u32 v[2:3], s[24:25], v2, s73, 0
	v_mov_b32_e32 v4, v3
	v_mad_u64_u32 v[4:5], s[24:25], v5, s73, v[4:5]
	v_mov_b32_e32 v3, v4
	v_lshl_add_u64 v[2:3], v[2:3], 2, v[6:7]
	global_load_dwordx4 v[2:5], v[2:3], off
	v_add_u32_e32 v242, 0x100, v8
	v_ashrrev_i32_e32 v242, 4, v242
	v_add_u32_e32 v242, s72, v242
	v_mul_lo_u32 v242, v242, s73
	v_mov_b32_e32 v243, 0
	v_lshl_add_u64 v[244:245], v[242:243], 2, v[6:7]
	global_load_dwordx4 v[230:233], v[244:245], off
	v_add_u32_e32 v242, 0x200, v8
	v_ashrrev_i32_e32 v242, 4, v242
	v_add_u32_e32 v242, s72, v242
	v_mul_lo_u32 v242, v242, s73
	v_mov_b32_e32 v243, 0
	v_lshl_add_u64 v[244:245], v[242:243], 2, v[6:7]
	global_load_dwordx4 v[234:237], v[244:245], off
	v_add_u32_e32 v242, 0x300, v8
	v_ashrrev_i32_e32 v242, 4, v242
	v_add_u32_e32 v242, s72, v242
	v_mul_lo_u32 v242, v242, s73
	v_mov_b32_e32 v243, 0
	v_lshl_add_u64 v[244:245], v[242:243], 2, v[6:7]
	global_load_dwordx4 v[238:241], v[244:245], off
.LBB0_122:
	s_or_b64 exec, exec, s[70:71]
	v_mad_u64_u32 v[10:11], s[24:25], v1, s82, v[72:73]
	s_waitcnt vmcnt(0)
	ds_write2_b32 v10, v2, v3 offset1:1
	ds_write2_b32 v10, v4, v5 offset0:2 offset1:3
	v_add_u32_e32 v10, 0x100, v8
	v_ashrrev_i32_e32 v4, 4, v10
	v_mov_b32_e32 v1, 0
	v_mov_b32_e32 v2, 0
	v_mov_b32_e32 v3, 0
	s_and_saveexec_b64 s[70:71], vcc
	s_cbranch_execz .LBB0_124
	v_add_u32_e32 v0, s72, v4
	v_ashrrev_i32_e32 v3, 31, v0
	v_mad_u64_u32 v[0:1], s[24:25], v0, s73, 0
	v_mov_b32_e32 v2, v1
	v_mad_u64_u32 v[2:3], s[24:25], v3, s73, v[2:3]
	v_mov_b32_e32 v1, v2
	v_lshl_add_u64 v[0:1], v[0:1], 2, v[6:7]
	v_mov_b32_e32 v0, v230
	v_mov_b32_e32 v1, v231
	v_mov_b32_e32 v2, v232
	v_mov_b32_e32 v3, v233
.LBB0_124:
	s_or_b64 exec, exec, s[70:71]
	v_mad_u64_u32 v[4:5], s[24:25], v4, s82, v[72:73]
	v_add_u32_e32 v9, 0x200, v8
	s_waitcnt vmcnt(0)
	ds_write2_b32 v4, v0, v1 offset1:1
	ds_write2_b32 v4, v2, v3 offset0:2 offset1:3
	v_ashrrev_i32_e32 v1, 4, v9
	v_mov_b32_e32 v0, 0
	v_mov_b32_e32 v2, 0
	v_mov_b32_e32 v3, 0
	v_mov_b32_e32 v4, 0
	v_mov_b32_e32 v5, 0
	s_and_saveexec_b64 s[70:71], vcc
	s_cbranch_execz .LBB0_126
	v_add_u32_e32 v2, s72, v1
	v_ashrrev_i32_e32 v5, 31, v2
	v_mad_u64_u32 v[2:3], s[24:25], v2, s73, 0
	v_mov_b32_e32 v4, v3
	v_mad_u64_u32 v[4:5], s[24:25], v5, s73, v[4:5]
	v_mov_b32_e32 v3, v4
	v_lshl_add_u64 v[2:3], v[2:3], 2, v[6:7]
	v_mov_b32_e32 v2, v234
	v_mov_b32_e32 v3, v235
	v_mov_b32_e32 v4, v236
	v_mov_b32_e32 v5, v237
.LBB0_126:
	s_or_b64 exec, exec, s[70:71]
	v_mad_u64_u32 v[12:13], s[24:25], v1, s82, v[72:73]
	s_waitcnt vmcnt(0)
	ds_write2_b32 v12, v2, v3 offset1:1
	ds_write2_b32 v12, v4, v5 offset0:2 offset1:3
	v_add_u32_e32 v4, 0x300, v8
	v_ashrrev_i32_e32 v5, 4, v4
	v_mov_b32_e32 v1, 0
	v_mov_b32_e32 v2, 0
	v_mov_b32_e32 v3, 0
	s_and_saveexec_b64 s[70:71], vcc
	s_cbranch_execz .LBB0_87
	v_add_u32_e32 v0, s72, v5
	v_ashrrev_i32_e32 v3, 31, v0
	v_mad_u64_u32 v[0:1], s[24:25], v0, s73, 0
	v_mov_b32_e32 v2, v1
	v_mad_u64_u32 v[2:3], s[24:25], v3, s73, v[2:3]
	v_mov_b32_e32 v1, v2
	v_lshl_add_u64 v[0:1], v[0:1], 2, v[6:7]
	v_mov_b32_e32 v0, v238
	v_mov_b32_e32 v1, v239
	v_mov_b32_e32 v2, v240
	v_mov_b32_e32 v3, v241
	s_branch .LBB0_87

.LBB0_1182:
	s_lshr_b32 s4, s72, 6
	s_mul_i32 s4, s6, s4
	s_add_i32 s7, s4, s35
	s_cmp_lt_i32 s26, s7
	s_cselect_b64 s[4:5], -1, 0
	s_cmp_ge_i32 s26, s7
	s_cbranch_scc1 .LBB0_1145
	v_cvt_f32_u32_e32 v0, s6
	s_sub_i32 s8, 0, s6
	s_sub_i32 s7, s26, s35
	s_abs_i32 s10, s7
	v_rcp_iflag_f32_e32 v0, v0
	s_ashr_i32 s9, s7, 31
	v_mov_b32_e32 v1, 0
	v_mul_f32_e32 v0, 0x4f7ffffe, v0
	v_cvt_u32_f32_e32 v0, v0
	v_mov_b32_e32 v2, 0
	v_mov_b32_e32 v3, 0
	v_mov_b32_e32 v4, 0
	v_readfirstlane_b32 s11, v0
	s_mul_i32 s8, s8, s11
	s_mul_hi_u32 s8, s11, s8
	s_add_i32 s11, s11, s8
	s_mul_hi_u32 s8, s10, s11
	s_mul_i32 s11, s8, s6
	s_sub_i32 s10, s10, s11
	s_add_i32 s24, s8, 1
	s_sub_i32 s11, s10, s6
	s_cmp_ge_u32 s10, s6
	s_cselect_b32 s8, s24, s8
	s_cselect_b32 s10, s11, s10
	s_add_i32 s11, s8, 1
	s_cmp_ge_u32 s10, s6
	s_cselect_b32 s8, s11, s8
	s_xor_b32 s8, s8, s9
	s_sub_i32 s8, s8, s9
	s_lshl_b32 s24, s8, 6
	s_mul_i32 s8, s8, s6
	s_sub_i32 s6, s7, s8
	v_mbcnt_lo_u32_b32 v0, -1, v1
	s_lshl_b32 s6, s6, 6
	v_mbcnt_hi_u32_b32 v0, -1, v0
	v_add_u32_e32 v8, s33, v0
	s_ashr_i32 s7, s6, 31
	s_lshl_b64 s[8:9], s[6:7], 2
	v_lshlrev_b32_e32 v0, 2, v8
	v_and_b32_e32 v0, 60, v0
	s_add_u32 s2, s2, s8
	v_or_b32_e32 v1, s6, v0
	s_addc_u32 s3, s3, s9
	v_lshlrev_b32_e32 v12, 2, v0
	v_cmp_gt_i32_e32 vcc, s25, v1
	v_lshl_add_u64 v[6:7], s[2:3], 0, v[12:13]
	v_ashrrev_i32_e32 v1, 4, v8
	v_mov_b32_e32 v0, 0
	v_mov_b32_e32 v5, 0
	s_waitcnt lgkmcnt(0)
	s_barrier
	v_mov_b32_e32 v230, 0
	v_mov_b32_e32 v231, 0
	v_mov_b32_e32 v232, 0
	v_mov_b32_e32 v233, 0
	v_mov_b32_e32 v234, 0
	v_mov_b32_e32 v235, 0
	v_mov_b32_e32 v236, 0
	v_mov_b32_e32 v237, 0
	v_mov_b32_e32 v238, 0
	v_mov_b32_e32 v239, 0
	v_mov_b32_e32 v240, 0
	v_mov_b32_e32 v241, 0
	s_and_saveexec_b64 s[2:3], vcc
	s_cbranch_execz .LBB0_1185
	v_add_u32_e32 v2, s24, v1
	v_ashrrev_i32_e32 v5, 31, v2
	v_mad_u64_u32 v[2:3], s[8:9], v2, s25, 0
	v_mov_b32_e32 v4, v3
	v_mad_u64_u32 v[4:5], s[8:9], v5, s25, v[4:5]
	v_mov_b32_e32 v3, v4
	v_lshl_add_u64 v[2:3], v[2:3], 2, v[6:7]
	global_load_dwordx4 v[2:5], v[2:3], off
	v_add_u32_e32 v242, 0x100, v8
	v_ashrrev_i32_e32 v242, 4, v242
	v_add_u32_e32 v242, s24, v242
	v_mul_lo_u32 v242, v242, s25
	v_mov_b32_e32 v243, 0
	v_lshl_add_u64 v[244:245], v[242:243], 2, v[6:7]
	global_load_dwordx4 v[230:233], v[244:245], off
	v_add_u32_e32 v242, 0x200, v8
	v_ashrrev_i32_e32 v242, 4, v242
	v_add_u32_e32 v242, s24, v242
	v_mul_lo_u32 v242, v242, s25
	v_mov_b32_e32 v243, 0
	v_lshl_add_u64 v[244:245], v[242:243], 2, v[6:7]
	global_load_dwordx4 v[234:237], v[244:245], off
	v_add_u32_e32 v242, 0x300, v8
	v_ashrrev_i32_e32 v242, 4, v242
	v_add_u32_e32 v242, s24, v242
	v_mul_lo_u32 v242, v242, s25
	v_mov_b32_e32 v243, 0
	v_lshl_add_u64 v[244:245], v[242:243], 2, v[6:7]
	global_load_dwordx4 v[238:241], v[244:245], off
.LBB0_1185:
	s_or_b64 exec, exec, s[2:3]
	v_mad_u64_u32 v[10:11], s[2:3], v1, s82, v[12:13]
	v_add_u32_e32 v9, 0x100, v8
	s_waitcnt vmcnt(0) lgkmcnt(0)
	ds_write2_b32 v10, v2, v3 offset1:1
	ds_write2_b32 v10, v4, v5 offset0:2 offset1:3
	v_ashrrev_i32_e32 v4, 4, v9
	v_mov_b32_e32 v1, 0
	v_mov_b32_e32 v2, 0
	v_mov_b32_e32 v3, 0
	s_and_saveexec_b64 s[2:3], vcc
	s_cbranch_execz .LBB0_1187
	v_add_u32_e32 v0, s24, v4
	v_ashrrev_i32_e32 v3, 31, v0
	v_mad_u64_u32 v[0:1], s[8:9], v0, s25, 0
	v_mov_b32_e32 v2, v1
	v_mad_u64_u32 v[2:3], s[8:9], v3, s25, v[2:3]
	v_mov_b32_e32 v1, v2
	v_lshl_add_u64 v[0:1], v[0:1], 2, v[6:7]
	v_mov_b32_e32 v0, v230
	v_mov_b32_e32 v1, v231
	v_mov_b32_e32 v2, v232
	v_mov_b32_e32 v3, v233
.LBB0_1187:
	s_or_b64 exec, exec, s[2:3]
	v_mad_u64_u32 v[4:5], s[2:3], v4, s82, v[12:13]
	v_add_u32_e32 v10, 0x200, v8
	s_waitcnt vmcnt(0) lgkmcnt(0)
	ds_write2_b32 v4, v0, v1 offset1:1
	ds_write2_b32 v4, v2, v3 offset0:2 offset1:3
	v_ashrrev_i32_e32 v1, 4, v10
	v_mov_b32_e32 v0, 0
	v_mov_b32_e32 v2, 0
	v_mov_b32_e32 v3, 0
	v_mov_b32_e32 v4, 0
	v_mov_b32_e32 v5, 0
	s_and_saveexec_b64 s[2:3], vcc
	s_cbranch_execz .LBB0_1189
	v_add_u32_e32 v2, s24, v1
	v_ashrrev_i32_e32 v5, 31, v2
	v_mad_u64_u32 v[2:3], s[8:9], v2, s25, 0
	v_mov_b32_e32 v4, v3
	v_mad_u64_u32 v[4:5], s[8:9], v5, s25, v[4:5]
	v_mov_b32_e32 v3, v4
	v_lshl_add_u64 v[2:3], v[2:3], 2, v[6:7]
	v_mov_b32_e32 v2, v234
	v_mov_b32_e32 v3, v235
	v_mov_b32_e32 v4, v236
	v_mov_b32_e32 v5, v237
.LBB0_1189:
	s_or_b64 exec, exec, s[2:3]
	v_mad_u64_u32 v[14:15], s[2:3], v1, s82, v[12:13]
	s_waitcnt vmcnt(0) lgkmcnt(0)
	ds_write2_b32 v14, v2, v3 offset1:1
	ds_write2_b32 v14, v4, v5 offset0:2 offset1:3
	v_add_u32_e32 v4, 0x300, v8
	v_ashrrev_i32_e32 v5, 4, v4
	v_mov_b32_e32 v1, 0
	v_mov_b32_e32 v2, 0
	v_mov_b32_e32 v3, 0
	s_and_saveexec_b64 s[2:3], vcc
	s_cbranch_execz .LBB0_1144
	v_add_u32_e32 v0, s24, v5
	v_ashrrev_i32_e32 v3, 31, v0
	v_mad_u64_u32 v[0:1], s[8:9], v0, s25, 0
	v_mov_b32_e32 v2, v1
	v_mad_u64_u32 v[2:3], s[8:9], v3, s25, v[2:3]
	v_mov_b32_e32 v1, v2
	v_lshl_add_u64 v[0:1], v[0:1], 2, v[6:7]
	v_mov_b32_e32 v0, v238
	v_mov_b32_e32 v1, v239
	v_mov_b32_e32 v2, v240
	v_mov_b32_e32 v3, v241
	s_branch .LBB0_1144
